# attention loops: running-max accumulator-init copies moved from each iteration to the loop exit
# speedup vs baseline: 1.0430x; 1.0039x over previous
.LBB0_936:
	v_mov_b64_e32 v[178:179], v[176:177]

.LBB0_939:
	v_mov_b64_e32 v[32:33], v[48:49]
	v_mov_b64_e32 v[34:35], v[50:51]
	v_mov_b64_e32 v[36:37], v[52:53]
	v_mov_b64_e32 v[38:39], v[54:55]
	v_mov_b64_e32 v[40:41], v[56:57]
	v_mov_b64_e32 v[42:43], v[58:59]
	v_mov_b64_e32 v[44:45], v[60:61]
	v_mov_b64_e32 v[46:47], v[62:63]
	s_waitcnt vmcnt(0)
	ds_write_b128 v186, v[132:135] offset:32768
	s_and_saveexec_b64 s[8:9], s[2:3]
	ds_write_b128 v169, v[124:127] offset:32768
	s_or_b64 exec, exec, s[8:9]
	s_and_saveexec_b64 s[2:3], s[4:5]
	s_cbranch_execz .LBB0_943
	v_perm_b32 v48, v120, v128, s85
	v_perm_b32 v49, v120, v128, s86
	v_add_u32_e32 v50, 0xb400, v182
	ds_write2_b32 v50, v48, v49 offset1:34
	v_perm_b32 v48, v121, v129, s85
	v_perm_b32 v49, v121, v129, s86
	ds_write2_b32 v50, v48, v49 offset0:68 offset1:102
	v_perm_b32 v48, v122, v130, s85
	v_perm_b32 v49, v122, v130, s86
	ds_write2_b32 v50, v48, v49 offset0:136 offset1:170
	v_perm_b32 v48, v123, v131, s85
	v_perm_b32 v49, v123, v131, s86
	ds_write2_b32 v50, v48, v49 offset0:204 offset1:238

.LBB0_961:
	v_mov_b64_e32 v[214:215], v[212:213]

.LBB0_964:
	v_mov_b64_e32 v[64:65], v[80:81]
	v_mov_b64_e32 v[66:67], v[82:83]
	v_mov_b64_e32 v[68:69], v[84:85]
	v_mov_b64_e32 v[70:71], v[86:87]
	v_mov_b64_e32 v[72:73], v[88:89]
	v_mov_b64_e32 v[74:75], v[90:91]
	v_mov_b64_e32 v[76:77], v[92:93]
	v_mov_b64_e32 v[78:79], v[94:95]
	s_waitcnt vmcnt(2)
	ds_write_b128 v222, v[148:151] offset:32768
	s_and_saveexec_b64 s[0:1], s[2:3]
	ds_write_b128 v192, v[144:147] offset:32768
	s_or_b64 exec, exec, s[0:1]
	s_waitcnt vmcnt(0)
	v_perm_b32 v80, v156, v152, s85
	v_perm_b32 v81, v156, v152, s86
	v_add_u32_e32 v82, 0xb400, v223
	ds_write2_b32 v82, v80, v81 offset1:34
	v_perm_b32 v80, v157, v153, s85
	v_perm_b32 v81, v157, v153, s86
	ds_write2_b32 v82, v80, v81 offset0:68 offset1:102
	v_perm_b32 v80, v158, v154, s85
	v_perm_b32 v81, v158, v154, s86
	ds_write2_b32 v82, v80, v81 offset0:136 offset1:170
	v_perm_b32 v80, v159, v155, s85
	v_perm_b32 v81, v159, v155, s86
	ds_write2_b32 v82, v80, v81 offset0:204 offset1:238
	v_add_u32_e32 v80, 0x8000, v242
	s_waitcnt lgkmcnt(0)
	s_barrier
	ds_read_b128 v[96:99], v80
	ds_read_b128 v[100:103], v80 offset:0x1200
	ds_read_b128 v[104:107], v80 offset:32
	ds_read_b128 v[108:111], v80 offset:0x1220
	ds_read_b128 v[112:115], v80 offset:64
	ds_read_b128 v[116:119], v80 offset:0x1240
	ds_read_b128 v[144:147], v80 offset:96
	ds_read_b128 v[120:123], v80 offset:0x1260
	s_waitcnt lgkmcnt(0)
	s_nop 0
	v_mfma_f32_32x32x16_bf16 v[80:95], v[96:99], v[140:143], v[64:79]
	v_mfma_f32_32x32x16_bf16 v[64:79], v[100:103], v[140:143], v[64:79]
	v_mfma_f32_32x32x16_bf16 v[80:95], v[104:107], v[136:139], v[80:95]
	v_mfma_f32_32x32x16_bf16 v[64:79], v[108:111], v[136:139], v[64:79]
	v_mfma_f32_32x32x16_bf16 v[80:95], v[112:115], v[132:135], v[80:95]
	v_mfma_f32_32x32x16_bf16 v[64:79], v[116:119], v[132:135], v[64:79]
	v_add_u32_e32 v132, 0xb400, v243
	v_mfma_f32_32x32x16_bf16 v[64:79], v[120:123], v[128:131], v[64:79]
	ds_read_b64 v[124:125], v132
	ds_read_b64 v[126:127], v132 offset:16
	ds_read_b64 v[120:121], v132 offset:32
	ds_read_b64 v[122:123], v132 offset:48
	ds_read_b64 v[116:117], v132 offset:64
	ds_read_b64 v[118:119], v132 offset:80
	ds_read_b64 v[112:113], v132 offset:96
	ds_read_b64 v[114:115], v132 offset:112
	ds_read_b64 v[108:109], v132 offset:0x1100
	ds_read_b64 v[110:111], v132 offset:0x1110
	ds_read_b64 v[104:105], v132 offset:0x1120
	ds_read_b64 v[106:107], v132 offset:0x1130
	ds_read_b64 v[100:101], v132 offset:0x1140
	ds_read_b64 v[102:103], v132 offset:0x1150
	ds_read_b64 v[96:97], v132 offset:0x1160
	ds_read_b64 v[98:99], v132 offset:0x1170
	v_mfma_f32_32x32x16_bf16 v[80:95], v[144:147], v[128:131], v[80:95]
	s_nop 10
	v_max_f32_e32 v133, v64, v64
	v_max_f32_e32 v129, v81, v65
	v_max_f32_e32 v130, v83, v67
	v_max_f32_e32 v128, v80, v133
	v_max3_f32 v130, v82, v66, v130
	v_max3_f32 v128, v128, v129, v130
	v_max_f32_e32 v129, v85, v69
	v_max_f32_e32 v130, v87, v71
	v_max3_f32 v129, v84, v68, v129
	v_max3_f32 v130, v86, v70, v130
	v_max3_f32 v128, v128, v129, v130
	v_max_f32_e32 v129, v89, v73
	v_max_f32_e32 v130, v91, v75
	v_max3_f32 v129, v88, v72, v129
	v_max3_f32 v130, v90, v74, v130
	v_max3_f32 v128, v128, v129, v130
	v_max_f32_e32 v129, v93, v77
	v_max_f32_e32 v131, v95, v95
	v_max_f32_e32 v130, v131, v79
	v_max3_f32 v129, v92, v76, v129
	v_max3_f32 v130, v94, v78, v130
	v_max3_f32 v128, v128, v129, v130
	v_mov_b32_e32 v129, v128
	s_nop 1
	v_permlane32_swap_b32_e32 v128, v129
	v_max_f32_e32 v128, v128, v129
	v_cmp_lt_f32_e32 vcc, s80, v128
	s_cbranch_vccz .LBB0_968
	v_max_f32_e32 v128, 0, v128
	v_exp_f32_e64 v130, -v128
	v_pk_add_f32 v[80:81], v[80:81], v[128:129] op_sel_hi:[1,0] neg_lo:[0,1] neg_hi:[0,1]
	v_pk_add_f32 v[64:65], v[64:65], v[128:129] op_sel_hi:[1,0] neg_lo:[0,1] neg_hi:[0,1]
	v_pk_add_f32 v[82:83], v[82:83], v[128:129] op_sel_hi:[1,0] neg_lo:[0,1] neg_hi:[0,1]
	v_pk_mul_f32 v[14:15], v[14:15], v[130:131] op_sel_hi:[1,0]
	v_pk_mul_f32 v[12:13], v[12:13], v[130:131] op_sel_hi:[1,0]
	v_pk_mul_f32 v[10:11], v[10:11], v[130:131] op_sel_hi:[1,0]
	v_pk_mul_f32 v[8:9], v[8:9], v[130:131] op_sel_hi:[1,0]
	v_pk_mul_f32 v[6:7], v[6:7], v[130:131] op_sel_hi:[1,0]
	v_pk_mul_f32 v[4:5], v[4:5], v[130:131] op_sel_hi:[1,0]
	v_pk_mul_f32 v[2:3], v[2:3], v[130:131] op_sel_hi:[1,0]
	v_pk_mul_f32 v[0:1], v[0:1], v[130:131] op_sel_hi:[1,0]
	v_pk_mul_f32 v[30:31], v[30:31], v[130:131] op_sel_hi:[1,0]
	v_pk_mul_f32 v[28:29], v[28:29], v[130:131] op_sel_hi:[1,0]
	v_pk_mul_f32 v[26:27], v[26:27], v[130:131] op_sel_hi:[1,0]
	v_pk_mul_f32 v[24:25], v[24:25], v[130:131] op_sel_hi:[1,0]
	v_pk_mul_f32 v[22:23], v[22:23], v[130:131] op_sel_hi:[1,0]
	v_pk_mul_f32 v[20:21], v[20:21], v[130:131] op_sel_hi:[1,0]
	v_pk_mul_f32 v[18:19], v[18:19], v[130:131] op_sel_hi:[1,0]
	v_pk_mul_f32 v[16:17], v[16:17], v[130:131] op_sel_hi:[1,0]
	v_pk_mul_f32 v[62:63], v[62:63], v[130:131] op_sel_hi:[1,0]
	v_pk_mul_f32 v[60:61], v[60:61], v[130:131] op_sel_hi:[1,0]
	v_pk_mul_f32 v[58:59], v[58:59], v[130:131] op_sel_hi:[1,0]
	v_pk_mul_f32 v[56:57], v[56:57], v[130:131] op_sel_hi:[1,0]
	v_pk_mul_f32 v[54:55], v[54:55], v[130:131] op_sel_hi:[1,0]
	v_pk_mul_f32 v[52:53], v[52:53], v[130:131] op_sel_hi:[1,0]
	v_pk_mul_f32 v[50:51], v[50:51], v[130:131] op_sel_hi:[1,0]
	v_pk_mul_f32 v[48:49], v[48:49], v[130:131] op_sel_hi:[1,0]
	v_pk_mul_f32 v[46:47], v[46:47], v[130:131] op_sel_hi:[1,0]
	v_pk_mul_f32 v[44:45], v[44:45], v[130:131] op_sel_hi:[1,0]
	v_pk_mul_f32 v[42:43], v[42:43], v[130:131] op_sel_hi:[1,0]
	v_pk_mul_f32 v[40:41], v[40:41], v[130:131] op_sel_hi:[1,0]
	v_pk_mul_f32 v[38:39], v[38:39], v[130:131] op_sel_hi:[1,0]
	v_pk_mul_f32 v[36:37], v[36:37], v[130:131] op_sel_hi:[1,0]
	v_pk_mul_f32 v[34:35], v[34:35], v[130:131] op_sel_hi:[1,0]
	v_pk_mul_f32 v[32:33], v[32:33], v[130:131] op_sel_hi:[1,0]
	v_mul_f32_e32 v160, v160, v130
	v_pk_add_f32 v[66:67], v[66:67], v[128:129] op_sel_hi:[1,0] neg_lo:[0,1] neg_hi:[0,1]
	v_pk_add_f32 v[84:85], v[84:85], v[128:129] op_sel_hi:[1,0] neg_lo:[0,1] neg_hi:[0,1]
	v_pk_add_f32 v[68:69], v[68:69], v[128:129] op_sel_hi:[1,0] neg_lo:[0,1] neg_hi:[0,1]
	v_pk_add_f32 v[86:87], v[86:87], v[128:129] op_sel_hi:[1,0] neg_lo:[0,1] neg_hi:[0,1]
	v_pk_add_f32 v[70:71], v[70:71], v[128:129] op_sel_hi:[1,0] neg_lo:[0,1] neg_hi:[0,1]
	v_pk_add_f32 v[88:89], v[88:89], v[128:129] op_sel_hi:[1,0] neg_lo:[0,1] neg_hi:[0,1]
	v_pk_add_f32 v[72:73], v[72:73], v[128:129] op_sel_hi:[1,0] neg_lo:[0,1] neg_hi:[0,1]
	v_pk_add_f32 v[90:91], v[90:91], v[128:129] op_sel_hi:[1,0] neg_lo:[0,1] neg_hi:[0,1]
	v_pk_add_f32 v[74:75], v[74:75], v[128:129] op_sel_hi:[1,0] neg_lo:[0,1] neg_hi:[0,1]
	v_pk_add_f32 v[92:93], v[92:93], v[128:129] op_sel_hi:[1,0] neg_lo:[0,1] neg_hi:[0,1]
	v_pk_add_f32 v[76:77], v[76:77], v[128:129] op_sel_hi:[1,0] neg_lo:[0,1] neg_hi:[0,1]
	v_pk_add_f32 v[94:95], v[94:95], v[128:129] op_sel_hi:[1,0] neg_lo:[0,1] neg_hi:[0,1]
	v_pk_add_f32 v[78:79], v[78:79], v[128:129] op_sel_hi:[1,0] neg_lo:[0,1] neg_hi:[0,1]

.LBB0_981:
	v_mov_b64_e32 v[212:213], v[210:211]

.LBB0_984:
	v_mov_b64_e32 v[64:65], v[80:81]
	v_mov_b64_e32 v[66:67], v[82:83]
	v_mov_b64_e32 v[68:69], v[84:85]
	v_mov_b64_e32 v[70:71], v[86:87]
	v_mov_b64_e32 v[72:73], v[88:89]
	v_mov_b64_e32 v[74:75], v[90:91]
	v_mov_b64_e32 v[76:77], v[92:93]
	v_mov_b64_e32 v[78:79], v[94:95]
	s_waitcnt vmcnt(2)
	ds_write_b128 v240, v[148:151] offset:32768
	s_and_saveexec_b64 s[0:1], s[2:3]
	ds_write_b128 v219, v[144:147] offset:32768
	s_or_b64 exec, exec, s[0:1]
	s_waitcnt vmcnt(0)
	v_perm_b32 v80, v156, v152, s85
	v_perm_b32 v81, v156, v152, s86
	v_add_u32_e32 v82, 0xb400, v241
	ds_write2_b32 v82, v80, v81 offset1:34
	v_perm_b32 v80, v157, v153, s85
	v_perm_b32 v81, v157, v153, s86
	ds_write2_b32 v82, v80, v81 offset0:68 offset1:102
	v_perm_b32 v80, v158, v154, s85
	v_perm_b32 v81, v158, v154, s86
	ds_write2_b32 v82, v80, v81 offset0:136 offset1:170
	v_perm_b32 v80, v159, v155, s85
	v_perm_b32 v81, v159, v155, s86
	ds_write2_b32 v82, v80, v81 offset0:204 offset1:238
	v_add_u32_e32 v80, 0x8000, v245
	s_waitcnt lgkmcnt(0)
	s_barrier
	ds_read_b128 v[96:99], v80
	ds_read_b128 v[100:103], v80 offset:0x1200
	ds_read_b128 v[104:107], v80 offset:32
	ds_read_b128 v[108:111], v80 offset:0x1220
	ds_read_b128 v[112:115], v80 offset:64
	ds_read_b128 v[116:119], v80 offset:0x1240
	ds_read_b128 v[144:147], v80 offset:96
	ds_read_b128 v[120:123], v80 offset:0x1260
	s_waitcnt lgkmcnt(0)
	s_nop 0
	v_mfma_f32_32x32x16_bf16 v[80:95], v[96:99], v[140:143], v[64:79]
	v_mfma_f32_32x32x16_bf16 v[64:79], v[100:103], v[140:143], v[64:79]
	v_mfma_f32_32x32x16_bf16 v[80:95], v[104:107], v[136:139], v[80:95]
	v_mfma_f32_32x32x16_bf16 v[64:79], v[108:111], v[136:139], v[64:79]
	v_mfma_f32_32x32x16_bf16 v[80:95], v[112:115], v[132:135], v[80:95]
	v_mfma_f32_32x32x16_bf16 v[64:79], v[116:119], v[132:135], v[64:79]
	v_add_u32_e32 v132, 0xb400, v248
	v_mfma_f32_32x32x16_bf16 v[64:79], v[120:123], v[128:131], v[64:79]
	ds_read_b64 v[124:125], v132
	ds_read_b64 v[126:127], v132 offset:16
	ds_read_b64 v[120:121], v132 offset:32
	ds_read_b64 v[122:123], v132 offset:48
	ds_read_b64 v[116:117], v132 offset:64
	ds_read_b64 v[118:119], v132 offset:80
	ds_read_b64 v[112:113], v132 offset:96
	ds_read_b64 v[114:115], v132 offset:112
	ds_read_b64 v[108:109], v132 offset:0x1100
	ds_read_b64 v[110:111], v132 offset:0x1110
	ds_read_b64 v[104:105], v132 offset:0x1120
	ds_read_b64 v[106:107], v132 offset:0x1130
	ds_read_b64 v[100:101], v132 offset:0x1140
	ds_read_b64 v[102:103], v132 offset:0x1150
	ds_read_b64 v[96:97], v132 offset:0x1160
	ds_read_b64 v[98:99], v132 offset:0x1170
	v_mfma_f32_32x32x16_bf16 v[80:95], v[144:147], v[128:131], v[80:95]
	s_nop 10
	v_max_f32_e32 v133, v64, v64
	v_max_f32_e32 v129, v81, v65
	v_max_f32_e32 v130, v83, v67
	v_max_f32_e32 v128, v80, v133
	v_max3_f32 v130, v82, v66, v130
	v_max3_f32 v128, v128, v129, v130
	v_max_f32_e32 v129, v85, v69
	v_max_f32_e32 v130, v87, v71
	v_max3_f32 v129, v84, v68, v129
	v_max3_f32 v130, v86, v70, v130
	v_max3_f32 v128, v128, v129, v130
	v_max_f32_e32 v129, v89, v73
	v_max_f32_e32 v130, v91, v75
	v_max3_f32 v129, v88, v72, v129
	v_max3_f32 v130, v90, v74, v130
	v_max3_f32 v128, v128, v129, v130
	v_max_f32_e32 v129, v93, v77
	v_max_f32_e32 v131, v95, v95
	v_max_f32_e32 v130, v131, v79
	v_max3_f32 v129, v92, v76, v129
	v_max3_f32 v130, v94, v78, v130
	v_max3_f32 v128, v128, v129, v130
	v_mov_b32_e32 v129, v128
	s_nop 1
	v_permlane32_swap_b32_e32 v128, v129
	v_max_f32_e32 v128, v128, v129
	v_cmp_lt_f32_e32 vcc, s80, v128
	s_cbranch_vccz .LBB0_822
	v_max_f32_e32 v128, 0, v128
	v_exp_f32_e64 v130, -v128
	v_pk_add_f32 v[80:81], v[80:81], v[128:129] op_sel_hi:[1,0] neg_lo:[0,1] neg_hi:[0,1]
	v_pk_add_f32 v[64:65], v[64:65], v[128:129] op_sel_hi:[1,0] neg_lo:[0,1] neg_hi:[0,1]
	v_pk_add_f32 v[82:83], v[82:83], v[128:129] op_sel_hi:[1,0] neg_lo:[0,1] neg_hi:[0,1]
	v_pk_mul_f32 v[14:15], v[14:15], v[130:131] op_sel_hi:[1,0]
	v_pk_mul_f32 v[12:13], v[12:13], v[130:131] op_sel_hi:[1,0]
	v_pk_mul_f32 v[10:11], v[10:11], v[130:131] op_sel_hi:[1,0]
	v_pk_mul_f32 v[8:9], v[8:9], v[130:131] op_sel_hi:[1,0]
	v_pk_mul_f32 v[6:7], v[6:7], v[130:131] op_sel_hi:[1,0]
	v_pk_mul_f32 v[4:5], v[4:5], v[130:131] op_sel_hi:[1,0]
	v_pk_mul_f32 v[2:3], v[2:3], v[130:131] op_sel_hi:[1,0]
	v_pk_mul_f32 v[0:1], v[0:1], v[130:131] op_sel_hi:[1,0]
	v_pk_mul_f32 v[62:63], v[62:63], v[130:131] op_sel_hi:[1,0]
	v_pk_mul_f32 v[60:61], v[60:61], v[130:131] op_sel_hi:[1,0]
	v_pk_mul_f32 v[58:59], v[58:59], v[130:131] op_sel_hi:[1,0]
	v_pk_mul_f32 v[56:57], v[56:57], v[130:131] op_sel_hi:[1,0]
	v_pk_mul_f32 v[54:55], v[54:55], v[130:131] op_sel_hi:[1,0]
	v_pk_mul_f32 v[52:53], v[52:53], v[130:131] op_sel_hi:[1,0]
	v_pk_mul_f32 v[50:51], v[50:51], v[130:131] op_sel_hi:[1,0]
	v_pk_mul_f32 v[48:49], v[48:49], v[130:131] op_sel_hi:[1,0]
	v_pk_mul_f32 v[46:47], v[46:47], v[130:131] op_sel_hi:[1,0]
	v_pk_mul_f32 v[44:45], v[44:45], v[130:131] op_sel_hi:[1,0]
	v_pk_mul_f32 v[42:43], v[42:43], v[130:131] op_sel_hi:[1,0]
	v_pk_mul_f32 v[40:41], v[40:41], v[130:131] op_sel_hi:[1,0]
	v_pk_mul_f32 v[38:39], v[38:39], v[130:131] op_sel_hi:[1,0]
	v_pk_mul_f32 v[36:37], v[36:37], v[130:131] op_sel_hi:[1,0]
	v_pk_mul_f32 v[34:35], v[34:35], v[130:131] op_sel_hi:[1,0]
	v_pk_mul_f32 v[32:33], v[32:33], v[130:131] op_sel_hi:[1,0]
	v_pk_mul_f32 v[30:31], v[30:31], v[130:131] op_sel_hi:[1,0]
	v_pk_mul_f32 v[28:29], v[28:29], v[130:131] op_sel_hi:[1,0]
	v_pk_mul_f32 v[26:27], v[26:27], v[130:131] op_sel_hi:[1,0]
	v_pk_mul_f32 v[24:25], v[24:25], v[130:131] op_sel_hi:[1,0]
	v_pk_mul_f32 v[22:23], v[22:23], v[130:131] op_sel_hi:[1,0]
	v_pk_mul_f32 v[20:21], v[20:21], v[130:131] op_sel_hi:[1,0]
	v_pk_mul_f32 v[18:19], v[18:19], v[130:131] op_sel_hi:[1,0]
	v_pk_mul_f32 v[16:17], v[16:17], v[130:131] op_sel_hi:[1,0]
	v_mul_f32_e32 v160, v160, v130
	v_pk_add_f32 v[66:67], v[66:67], v[128:129] op_sel_hi:[1,0] neg_lo:[0,1] neg_hi:[0,1]
	v_pk_add_f32 v[84:85], v[84:85], v[128:129] op_sel_hi:[1,0] neg_lo:[0,1] neg_hi:[0,1]
	v_pk_add_f32 v[68:69], v[68:69], v[128:129] op_sel_hi:[1,0] neg_lo:[0,1] neg_hi:[0,1]
	v_pk_add_f32 v[86:87], v[86:87], v[128:129] op_sel_hi:[1,0] neg_lo:[0,1] neg_hi:[0,1]
	v_pk_add_f32 v[70:71], v[70:71], v[128:129] op_sel_hi:[1,0] neg_lo:[0,1] neg_hi:[0,1]
	v_pk_add_f32 v[88:89], v[88:89], v[128:129] op_sel_hi:[1,0] neg_lo:[0,1] neg_hi:[0,1]
	v_pk_add_f32 v[72:73], v[72:73], v[128:129] op_sel_hi:[1,0] neg_lo:[0,1] neg_hi:[0,1]
	v_pk_add_f32 v[90:91], v[90:91], v[128:129] op_sel_hi:[1,0] neg_lo:[0,1] neg_hi:[0,1]
	v_pk_add_f32 v[74:75], v[74:75], v[128:129] op_sel_hi:[1,0] neg_lo:[0,1] neg_hi:[0,1]
	v_pk_add_f32 v[92:93], v[92:93], v[128:129] op_sel_hi:[1,0] neg_lo:[0,1] neg_hi:[0,1]
	v_pk_add_f32 v[76:77], v[76:77], v[128:129] op_sel_hi:[1,0] neg_lo:[0,1] neg_hi:[0,1]
	v_pk_add_f32 v[94:95], v[94:95], v[128:129] op_sel_hi:[1,0] neg_lo:[0,1] neg_hi:[0,1]
	v_pk_add_f32 v[78:79], v[78:79], v[128:129] op_sel_hi:[1,0] neg_lo:[0,1] neg_hi:[0,1]
	s_branch .LBB0_822
